# v078 + GEMM epilogue store coalescing (ds_bpermute lane transpose so 4 adjacent lanes write 64 contiguous bytes) in P1 and P3
# speedup vs baseline: 1.0184x; 1.0059x over previous
; #define G_STAGE(bufoff, gbase, voff) do { _Pragma("unroll") for (int _i = 0; _i < 2; ++_i) \
;         __builtin_amdgcn_global_load_lds((const unsigned*)((const char*)(gbase) + (voff)[_i]), (LAS unsigned*)(lds + (bufoff) + ldsw + _i * 8192), 16, 0, 0); } while (0)
; #define G_WAIT_V(n) asm volatile("s_waitcnt vmcnt(" #n ")" ::: "memory")
; #define G_BAR __builtin_amdgcn_s_barrier()
; template <bool PERM, class Dec, class Epi>
; DI void gemm_phase(LAS unsigned char* lds, const int nM, const int nN, const int K, const int lda, const int ldb, const Dec& dec, const Epi& epi, const int vb, const int panel = -1) {
;     ...
;     G_STAGE(G_SB(0, 0), cB, voffB); G_STAGE(G_SA(0, 0), cA, voffA); G_STAGE(G_SB(0, 1), cB + hstepB, voffB); G_STAGE(G_SA(0, 1), cA + hstepA, voffA);
;     if (wr == 1) G_BAR;
;     G_WAIT_V(4); G_BAR;
;     G_STAGE(G_SB(1, 0), cB + kstep, voffB); G_STAGE(G_SA(1, 0), cA + kstep, voffA); G_STAGE(G_SB(1, 1), cB + hstepB + kstep, voffB);
;     G_WAIT_V(6); G_BAR;
; template <int ACT>
; DI void epi_bf16(const f32x4 (&acc)[2][2][4][2], bf16_t* O, const int ldc, int wr, int wc, int fr, int fq, const float* ssrow = nullptr) {
; #pragma unroll
;     for (int ai = 0; ai < 2; ++ai)
; #pragma unroll
;         for (int m = 0; m < 4; ++m) {
;             bf16_t* rowp = O + (size_t)(ai * HALF + wr * 64 + m * 16 + fr) * ldc + wc * 32 + 8 * fq;
.LBB0_178:
	v_mov_b32_e32 v139, v129
	v_lshl_add_u64 v[8:9], s[4:5], 0, v[138:139]
	v_mov_b32_e32 v135, v129
	v_lshl_add_u64 v[10:11], s[4:5], 0, v[134:135]
	v_mov_b32_e32 v141, v129
	s_add_i32 m0, s56, 0x18000
	v_lshl_add_u64 v[8:9], v[8:9], 0, s[30:31]
	v_lshl_add_u64 v[12:13], s[6:7], 0, v[140:141]
	v_mov_b32_e32 v137, v129
	s_waitcnt vmcnt(4)
	s_barrier
	global_load_lds_dwordx4 v[8:9], off
	v_lshl_add_u64 v[8:9], v[10:11], 0, s[30:31]
	s_add_i32 m0, s56, 0x1a000
	s_add_i32 s60, s56, 0x8000
	v_lshl_add_u64 v[14:15], s[6:7], 0, v[136:137]
	global_load_lds_dwordx4 v[8:9], off
	v_lshl_add_u64 v[8:9], v[12:13], 0, s[30:31]
	s_mov_b32 m0, s60
	s_add_i32 s61, s56, 0xa000
	global_load_lds_dwordx4 v[8:9], off
	v_lshl_add_u64 v[8:9], v[14:15], 0, s[30:31]
	s_mov_b32 m0, s61
	s_lshl_b32 s2, s2, 5
	global_load_lds_dwordx4 v[8:9], off
	s_add_i32 m0, s56, 0x1c000
	v_lshl_add_u64 v[8:9], s[28:29], 0, v[138:139]
	global_load_lds_dwordx4 v[8:9], off
	v_lshl_add_u64 v[8:9], s[28:29], 0, v[134:135]
	s_add_i32 m0, s56, 0x1e000
	v_and_b32_e32 v7, 15, v3
	global_load_lds_dwordx4 v[8:9], off
	v_lshrrev_b32_e32 v9, 1, v3
	v_and_b32_e32 v10, 24, v9
	v_lshlrev_b32_e32 v9, 1, v10
	v_lshlrev_b32_e32 v3, 2, v3
	s_and_b32 s22, s2, 0x60
	v_bfe_u32 v8, v3, 4, 4
	v_lshl_or_b32 v8, s3, 6, v8
	v_lshl_or_b32 v7, v7, 6, v9
	s_lshl_b32 s3, s3, 13
	v_and_b32_e32 v3, 32, v3
	s_lshl_b32 s2, s22, 7
	v_bitop3_b32 v11, v7, s3, v3 bitop3:0xde
	v_bitop3_b32 v163, v7, s2, v3 bitop3:0xde
	v_lshlrev_b32_e32 v3, 14, v5
	v_and_b32_e32 v3, 0xffff8000, v3
	v_lshl_add_u32 v3, v4, 11, v3
	v_and_b32_e32 v4, 1, v5
	v_ashrrev_i32_e32 v9, 31, v8
	v_lshl_or_b32 v3, v4, 6, v3
	v_lshlrev_b64 v[142:143], 12, v[8:9]
	v_or_b32_e32 v12, 16, v8
	s_mov_b64 s[2:3], 0x80000
	v_lshl_add_u32 v158, v6, 1, v3
	v_lshlrev_b32_e32 v3, 14, v0
	v_ashrrev_i32_e32 v13, 31, v12
	v_lshl_add_u64 v[150:151], v[142:143], 0, s[2:3]
	s_mov_b64 s[2:3], 0x90000
	v_and_b32_e32 v3, 0xffff8000, v3
	s_waitcnt vmcnt(6)
	v_lshlrev_b64 v[144:145], 12, v[12:13]
	v_or_b32_e32 v12, 32, v8
	v_or_b32_e32 v8, 48, v8
	v_lshl_add_u64 v[152:153], v[142:143], 0, s[2:3]
	s_mov_b64 s[2:3], 0xa0000
	v_lshl_add_u32 v1, v1, 11, v3
	v_and_b32_e32 v0, 1, v0
	v_ashrrev_i32_e32 v13, 31, v12
	v_ashrrev_i32_e32 v9, 31, v8
	v_lshl_add_u64 v[154:155], v[142:143], 0, s[2:3]
	s_mov_b64 s[2:3], 0xb0000
	v_lshl_or_b32 v0, v0, 6, v1
	v_lshlrev_b64 v[146:147], 12, v[12:13]
	v_lshlrev_b64 v[148:149], 12, v[8:9]
	v_lshl_add_u64 v[156:157], v[142:143], 0, s[2:3]
	v_mov_b32_e32 v159, v129
	v_lshl_add_u32 v160, v2, 1, v0
	v_mov_b32_e32 v161, v129
	s_mov_b32 s66, 0
	v_add_u32_e32 v164, 0, v11
	s_lshl_b32 s67, s22, 1
	v_mbcnt_lo_u32_b32 v241, -1, 0
	v_mbcnt_hi_u32_b32 v241, -1, v241
	v_and_b32_e32 v128, 3, v241
	v_lshlrev_b32_e32 v128, 4, v128
	v_and_b32_e32 v241, 60, v241
	v_lshl_or_b32 v241, v128, 2, v241
	s_mov_b32 s22, s0
	s_mov_b32 s70, s33
	s_mov_b64 s[44:45], s[6:7]
	s_mov_b64 s[46:47], s[4:5]
	s_barrier

; #define G_STAGE(bufoff, gbase, voff) do { _Pragma("unroll") for (int _i = 0; _i < 2; ++_i) \
;         __builtin_amdgcn_global_load_lds((const unsigned*)((const char*)(gbase) + (voff)[_i]), (LAS unsigned*)(lds + (bufoff) + ldsw + _i * 8192), 16, 0, 0); } while (0)
; #define G_LDA(dst, b, h) do { _Pragma("unroll") for (int m = 0; m < 4; ++m) _Pragma("unroll") for (int k = 0; k < 2; ++k) dst[m][k] = *(const LAS bf16x8*)(lds + G_SA(b, h) + aoff + m * 2048 + k * 1024); } while (0)
; #define G_LDB(dst, b, h) do { _Pragma("unroll") for (int n = 0; n < 2; ++n) _Pragma("unroll") for (int k = 0; k < 2; ++k) dst[n][k] = *(const LAS bf16x8*)(lds + G_SB(b, h) + boff + n * 2048 + k * 1024); } while (0)
; #define G_MMA(ai, bj, At, Bt) do { __builtin_amdgcn_s_setprio(1); _Pragma("unroll") for (int m = 0; m < 4; ++m) _Pragma("unroll") for (int n = 0; n < 2; ++n) _Pragma("unroll") for (int k = 0; k < 2; ++k) \
;         acc[ai][bj][m][n] = __builtin_amdgcn_mfma_f32_16x16x32_bf16(Bt[n][k], At[m][k], acc[ai][bj][m][n], 0, 0, 0); __builtin_amdgcn_s_setprio(0); } while (0)
; #define G_WAIT_V(n) asm volatile("s_waitcnt vmcnt(" #n ")" ::: "memory")
; #define G_WAIT_L(n) asm volatile("s_waitcnt lgkmcnt(" #n ")" ::: "memory")
; #define G_BAR __builtin_amdgcn_s_barrier()
; #define G_SCHED __builtin_amdgcn_sched_barrier(0)
; template <bool PERM, class Dec, class Epi>
; DI void gemm_phase(LAS unsigned char* lds, const int nM, const int nN, const int K, const int lda, const int ldb, const Dec& dec, const Epi& epi, const int vb, const int panel = -1) {
;     ...
;             G_LDB(B0, 0, 0); G_SCHED; G_LDA(At, 0, 0); G_STAGE(G_SA(1, 1), a1 + hstepA, voffA);
;             G_WAIT_L(8); G_BAR; G_WAIT_L(0); G_MMA(0, 0, At, B0); G_BAR; G_SCHED;
;             G_LDB(B1, 0, 1); G_STAGE(G_SB(0, 0), b2, voffB);
;             G_BAR; G_WAIT_L(0); G_MMA(0, 1, At, B1); G_BAR;
;             G_LDA(At, 0, 1); G_STAGE(G_SA(0, 0), a2, voffA);
;             G_BAR; G_WAIT_L(0); G_MMA(1, 0, At, B0); G_BAR; G_SCHED;
;             G_STAGE(G_SB(0, 1), b2 + hstepB, voffB);
;             G_WAIT_V(6); G_BAR; G_MMA(1, 1, At, B1); G_BAR;
.LBB0_182:
	s_add_u32 s46, s44, 0xfffc0080
	s_addc_u32 s47, s45, -1
	s_add_i32 s64, 0, 0x10000
	v_add_u32_e32 v165, s64, v163
	ds_read_b128 v[166:169], v165
	ds_read_b128 v[170:173], v165 offset:1024
	ds_read_b128 v[174:177], v165 offset:2048
	ds_read_b128 v[178:181], v165 offset:3072
	s_cmp_eq_u32 s79, 12
	s_cselect_b32 s49, s3, s47
	s_cselect_b32 s48, s23, s46
	s_cselect_b32 s47, s35, s77
	s_cselect_b32 s46, s71, s76
	v_lshl_add_u64 v[190:191], s[44:45], 0, v[158:159]
	s_add_i32 m0, s56, 0xc000
	ds_read_b128 v[182:185], v164
	ds_read_b128 v[186:189], v164 offset:1024
	ds_read_b128 v[194:197], v164 offset:2048
	ds_read_b128 v[198:201], v164 offset:3072
	ds_read_b128 v[202:205], v164 offset:4096
	ds_read_b128 v[206:209], v164 offset:5120
	ds_read_b128 v[210:213], v164 offset:6144
	ds_read_b128 v[214:217], v164 offset:7168
	global_load_lds_dwordx4 v[190:191], off
	v_lshl_add_u64 v[190:191], s[44:45], 0, v[160:161]
	s_add_i32 m0, s56, 0xe000
	s_nop 0
	global_load_lds_dwordx4 v[190:191], off
	s_waitcnt lgkmcnt(8)
	s_barrier
	s_waitcnt lgkmcnt(0)
	s_setprio 1
	s_waitcnt lgkmcnt(0)
	v_mfma_f32_16x16x32_bf16 v[124:127], v[166:169], v[182:185], v[124:127]
	v_mfma_f32_16x16x32_bf16 v[120:123], v[174:177], v[182:185], v[120:123]
	v_mfma_f32_16x16x32_bf16 v[116:119], v[166:169], v[194:197], v[116:119]
	v_mfma_f32_16x16x32_bf16 v[112:115], v[174:177], v[194:197], v[112:115]
	v_mfma_f32_16x16x32_bf16 v[100:103], v[166:169], v[202:205], v[100:103]
	v_mfma_f32_16x16x32_bf16 v[96:99], v[174:177], v[202:205], v[96:99]
	v_mfma_f32_16x16x32_bf16 v[84:87], v[166:169], v[210:213], v[84:87]
	v_mfma_f32_16x16x32_bf16 v[80:83], v[174:177], v[210:213], v[80:83]
	v_mfma_f32_16x16x32_bf16 v[124:127], v[170:173], v[186:189], v[124:127]
	v_mfma_f32_16x16x32_bf16 v[120:123], v[178:181], v[186:189], v[120:123]
	v_mfma_f32_16x16x32_bf16 v[116:119], v[170:173], v[198:201], v[116:119]
	v_mfma_f32_16x16x32_bf16 v[112:115], v[178:181], v[198:201], v[112:115]
	v_mfma_f32_16x16x32_bf16 v[100:103], v[170:173], v[206:209], v[100:103]
	v_mfma_f32_16x16x32_bf16 v[96:99], v[178:181], v[206:209], v[96:99]
	v_mfma_f32_16x16x32_bf16 v[84:87], v[170:173], v[214:217], v[84:87]
	v_mfma_f32_16x16x32_bf16 v[80:83], v[178:181], v[214:217], v[80:83]
	s_setprio 0
	s_barrier
	s_add_i32 s68, 0, 0x14000
	s_add_i32 s64, s64, s55
	v_add_u32_e32 v165, s68, v163
	v_lshl_add_u64 v[190:191], s[46:47], 0, v[138:139]
	s_mov_b32 m0, s64
	ds_read_b128 v[218:221], v165
	ds_read_b128 v[222:225], v165 offset:1024
	ds_read_b128 v[226:229], v165 offset:2048
	ds_read_b128 v[230:233], v165 offset:3072
	global_load_lds_dwordx4 v[190:191], off
	v_lshl_add_u64 v[234:235], s[46:47], 0, v[134:135]
	s_add_i32 m0, s64, 0x2000
	s_nop 0
	global_load_lds_dwordx4 v[234:235], off
	s_barrier
	s_waitcnt lgkmcnt(0)
	s_setprio 1
	s_waitcnt lgkmcnt(0)
	v_mfma_f32_16x16x32_bf16 v[108:111], v[218:221], v[182:185], v[108:111]
	v_mfma_f32_16x16x32_bf16 v[104:107], v[226:229], v[182:185], v[104:107]
	v_mfma_f32_16x16x32_bf16 v[92:95], v[218:221], v[194:197], v[92:95]
	v_mfma_f32_16x16x32_bf16 v[88:91], v[226:229], v[194:197], v[88:91]
	v_mfma_f32_16x16x32_bf16 v[76:79], v[218:221], v[202:205], v[76:79]
	v_mfma_f32_16x16x32_bf16 v[72:75], v[226:229], v[202:205], v[72:75]
	v_mfma_f32_16x16x32_bf16 v[68:71], v[218:221], v[210:213], v[68:71]
	v_mfma_f32_16x16x32_bf16 v[64:67], v[226:229], v[210:213], v[64:67]
	v_mfma_f32_16x16x32_bf16 v[108:111], v[222:225], v[186:189], v[108:111]
	v_mfma_f32_16x16x32_bf16 v[104:107], v[230:233], v[186:189], v[104:107]
	v_mfma_f32_16x16x32_bf16 v[92:95], v[222:225], v[198:201], v[92:95]
	v_mfma_f32_16x16x32_bf16 v[88:91], v[230:233], v[198:201], v[88:91]
	v_mfma_f32_16x16x32_bf16 v[76:79], v[222:225], v[206:209], v[76:79]
	v_mfma_f32_16x16x32_bf16 v[72:75], v[230:233], v[206:209], v[72:75]
	v_mfma_f32_16x16x32_bf16 v[68:71], v[222:225], v[214:217], v[68:71]
	v_mfma_f32_16x16x32_bf16 v[64:67], v[230:233], v[214:217], v[64:67]
	s_setprio 0
	s_mov_b32 m0, s56
	v_lshl_add_u64 v[236:237], s[48:49], 0, v[140:141]
	s_barrier
	ds_read_b128 v[182:185], v164 offset:16384
	ds_read_b128 v[186:189], v164 offset:17408
	ds_read_b128 v[194:197], v164 offset:18432
	ds_read_b128 v[198:201], v164 offset:19456
	ds_read_b128 v[202:205], v164 offset:20480
	ds_read_b128 v[206:209], v164 offset:21504
	ds_read_b128 v[210:213], v164 offset:22528
	ds_read_b128 v[214:217], v164 offset:23552
	global_load_lds_dwordx4 v[236:237], off
	v_lshl_add_u64 v[238:239], s[48:49], 0, v[136:137]
	s_mov_b32 m0, s57
	s_nop 0
	global_load_lds_dwordx4 v[238:239], off
	s_barrier
	s_waitcnt lgkmcnt(0)
	s_setprio 1
	s_waitcnt lgkmcnt(0)
	v_mfma_f32_16x16x32_bf16 v[60:63], v[166:169], v[182:185], v[60:63]
	v_mfma_f32_16x16x32_bf16 v[56:59], v[174:177], v[182:185], v[56:59]
	v_mfma_f32_16x16x32_bf16 v[52:55], v[166:169], v[194:197], v[52:55]
	v_mfma_f32_16x16x32_bf16 v[48:51], v[174:177], v[194:197], v[48:51]
	v_mfma_f32_16x16x32_bf16 v[36:39], v[166:169], v[202:205], v[36:39]
	v_mfma_f32_16x16x32_bf16 v[32:35], v[174:177], v[202:205], v[32:35]
	v_mfma_f32_16x16x32_bf16 v[20:23], v[166:169], v[210:213], v[20:23]
	v_mfma_f32_16x16x32_bf16 v[16:19], v[174:177], v[210:213], v[16:19]
	v_mfma_f32_16x16x32_bf16 v[60:63], v[170:173], v[186:189], v[60:63]
	v_mfma_f32_16x16x32_bf16 v[56:59], v[178:181], v[186:189], v[56:59]
	v_mfma_f32_16x16x32_bf16 v[52:55], v[170:173], v[198:201], v[52:55]
	v_mfma_f32_16x16x32_bf16 v[48:51], v[178:181], v[198:201], v[48:51]
	v_mfma_f32_16x16x32_bf16 v[36:39], v[170:173], v[206:209], v[36:39]
	v_mfma_f32_16x16x32_bf16 v[32:35], v[178:181], v[206:209], v[32:35]
	v_mfma_f32_16x16x32_bf16 v[20:23], v[170:173], v[214:217], v[20:23]
	v_mfma_f32_16x16x32_bf16 v[16:19], v[178:181], v[214:217], v[16:19]
	s_setprio 0
	s_barrier
; #define G_STAGE(bufoff, gbase, voff) do { _Pragma("unroll") for (int _i = 0; _i < 2; ++_i) \
;         __builtin_amdgcn_global_load_lds((const unsigned*)((const char*)(gbase) + (voff)[_i]), (LAS unsigned*)(lds + (bufoff) + ldsw + _i * 8192), 16, 0, 0); } while (0)
; #define G_LDA(dst, b, h) do { _Pragma("unroll") for (int m = 0; m < 4; ++m) _Pragma("unroll") for (int k = 0; k < 2; ++k) dst[m][k] = *(const LAS bf16x8*)(lds + G_SA(b, h) + aoff + m * 2048 + k * 1024); } while (0)
; #define G_LDB(dst, b, h) do { _Pragma("unroll") for (int n = 0; n < 2; ++n) _Pragma("unroll") for (int k = 0; k < 2; ++k) dst[n][k] = *(const LAS bf16x8*)(lds + G_SB(b, h) + boff + n * 2048 + k * 1024); } while (0)
; #define G_MMA(ai, bj, At, Bt) do { __builtin_amdgcn_s_setprio(1); _Pragma("unroll") for (int m = 0; m < 4; ++m) _Pragma("unroll") for (int n = 0; n < 2; ++n) _Pragma("unroll") for (int k = 0; k < 2; ++k) \
;         acc[ai][bj][m][n] = __builtin_amdgcn_mfma_f32_16x16x32_bf16(Bt[n][k], At[m][k], acc[ai][bj][m][n], 0, 0, 0); __builtin_amdgcn_s_setprio(0); } while (0)
; #define G_WAIT_V(n) asm volatile("s_waitcnt vmcnt(" #n ")" ::: "memory")
; #define G_WAIT_L(n) asm volatile("s_waitcnt lgkmcnt(" #n ")" ::: "memory")
; #define G_BAR __builtin_amdgcn_s_barrier()
; #define G_SCHED __builtin_amdgcn_sched_barrier(0)
; template <bool PERM, class Dec, class Epi>
; DI void gemm_phase(LAS unsigned char* lds, const int nM, const int nN, const int K, const int lda, const int ldb, const Dec& dec, const Epi& epi, const int vb, const int panel = -1) {
;     ...
;             G_WAIT_V(6); G_BAR; G_MMA(1, 1, At, B1); G_BAR;
;             G_LDB(B0, 1, 0); G_SCHED; G_LDA(At, 1, 0); G_STAGE(G_SA(0, 1), a2 + hstepA, voffA);
;             G_WAIT_L(8); G_BAR; G_WAIT_L(0); G_MMA(0, 0, At, B0); G_BAR; G_SCHED;
;             G_LDB(B1, 1, 1); G_STAGE(G_SB(1, 0), b3, voffB);
;             G_BAR; G_WAIT_L(0); G_MMA(0, 1, At, B1); G_BAR;
;             G_LDA(At, 1, 1); G_STAGE(G_SA(1, 0), a3, voffA);
;             G_BAR; G_WAIT_L(0); G_MMA(1, 0, At, B0); G_BAR; G_SCHED;
	s_add_u32 s64, s46, 0x40000
	s_addc_u32 s65, s47, 0
	s_add_i32 s68, s68, s55
	v_lshl_add_u64 v[166:167], s[64:65], 0, v[138:139]
	s_mov_b32 m0, s68
	s_nop 0
	global_load_lds_dwordx4 v[166:167], off
	v_lshl_add_u64 v[166:167], s[64:65], 0, v[134:135]
	s_add_i32 m0, s68, 0x2000
	s_nop 0
	global_load_lds_dwordx4 v[166:167], off
	s_waitcnt vmcnt(6)
	s_barrier
	s_setprio 1
	v_mfma_f32_16x16x32_bf16 v[44:47], v[218:221], v[182:185], v[44:47]
	v_mfma_f32_16x16x32_bf16 v[40:43], v[226:229], v[182:185], v[40:43]
	v_mfma_f32_16x16x32_bf16 v[28:31], v[218:221], v[194:197], v[28:31]
	v_mfma_f32_16x16x32_bf16 v[24:27], v[226:229], v[194:197], v[24:27]
	v_mfma_f32_16x16x32_bf16 v[12:15], v[218:221], v[202:205], v[12:15]
	v_mfma_f32_16x16x32_bf16 v[8:11], v[226:229], v[202:205], v[8:11]
	v_mfma_f32_16x16x32_bf16 v[4:7], v[218:221], v[210:213], v[4:7]
	v_mfma_f32_16x16x32_bf16 v[0:3], v[226:229], v[210:213], v[0:3]
	v_mfma_f32_16x16x32_bf16 v[44:47], v[222:225], v[186:189], v[44:47]
	v_mfma_f32_16x16x32_bf16 v[40:43], v[230:233], v[186:189], v[40:43]
	v_mfma_f32_16x16x32_bf16 v[28:31], v[222:225], v[198:201], v[28:31]
	v_mfma_f32_16x16x32_bf16 v[24:27], v[230:233], v[198:201], v[24:27]
	v_mfma_f32_16x16x32_bf16 v[12:15], v[222:225], v[206:209], v[12:15]
	v_mfma_f32_16x16x32_bf16 v[8:11], v[230:233], v[206:209], v[8:11]
	v_mfma_f32_16x16x32_bf16 v[4:7], v[222:225], v[214:217], v[4:7]
	v_mfma_f32_16x16x32_bf16 v[0:3], v[230:233], v[214:217], v[0:3]
	s_setprio 0
	s_add_i32 s64, 0, 0x18000
	v_add_u32_e32 v165, s64, v163
	s_barrier
	ds_read_b128 v[166:169], v165
	ds_read_b128 v[170:173], v165 offset:1024
	ds_read_b128 v[174:177], v165 offset:2048
	ds_read_b128 v[178:181], v165 offset:3072
	s_add_u32 s48, s48, 0x40000
	s_addc_u32 s49, s49, 0
	s_mov_b32 m0, s58
	v_lshl_add_u64 v[218:219], s[48:49], 0, v[140:141]
	ds_read_b128 v[182:185], v164 offset:32768
	ds_read_b128 v[186:189], v164 offset:33792
	ds_read_b128 v[194:197], v164 offset:34816
	ds_read_b128 v[198:201], v164 offset:35840
	ds_read_b128 v[202:205], v164 offset:36864
	ds_read_b128 v[206:209], v164 offset:37888
	ds_read_b128 v[210:213], v164 offset:38912
	ds_read_b128 v[214:217], v164 offset:39936
	global_load_lds_dwordx4 v[218:219], off
	v_lshl_add_u64 v[218:219], s[48:49], 0, v[136:137]
	s_mov_b32 m0, s59
	s_nop 0
	global_load_lds_dwordx4 v[218:219], off
	s_waitcnt lgkmcnt(8)
	s_barrier
	s_waitcnt lgkmcnt(0)
	s_setprio 1
	s_waitcnt lgkmcnt(0)
	v_mfma_f32_16x16x32_bf16 v[124:127], v[166:169], v[182:185], v[124:127]
	v_mfma_f32_16x16x32_bf16 v[120:123], v[174:177], v[182:185], v[120:123]
	v_mfma_f32_16x16x32_bf16 v[116:119], v[166:169], v[194:197], v[116:119]
	v_mfma_f32_16x16x32_bf16 v[112:115], v[174:177], v[194:197], v[112:115]
	v_mfma_f32_16x16x32_bf16 v[100:103], v[166:169], v[202:205], v[100:103]
	v_mfma_f32_16x16x32_bf16 v[96:99], v[174:177], v[202:205], v[96:99]
	v_mfma_f32_16x16x32_bf16 v[84:87], v[166:169], v[210:213], v[84:87]
	v_mfma_f32_16x16x32_bf16 v[80:83], v[174:177], v[210:213], v[80:83]
	v_mfma_f32_16x16x32_bf16 v[124:127], v[170:173], v[186:189], v[124:127]
	v_mfma_f32_16x16x32_bf16 v[120:123], v[178:181], v[186:189], v[120:123]
	v_mfma_f32_16x16x32_bf16 v[116:119], v[170:173], v[198:201], v[116:119]
	v_mfma_f32_16x16x32_bf16 v[112:115], v[178:181], v[198:201], v[112:115]
	v_mfma_f32_16x16x32_bf16 v[100:103], v[170:173], v[206:209], v[100:103]
	v_mfma_f32_16x16x32_bf16 v[96:99], v[178:181], v[206:209], v[96:99]
	v_mfma_f32_16x16x32_bf16 v[84:87], v[170:173], v[214:217], v[84:87]
	v_mfma_f32_16x16x32_bf16 v[80:83], v[178:181], v[214:217], v[80:83]
	s_setprio 0
	s_barrier
	s_add_i32 s48, 0, 0x1c000
	s_add_i32 s49, s64, s55
	v_add_u32_e32 v165, s48, v163
	v_lshl_add_u64 v[190:191], v[190:191], 0, s[30:31]
	s_mov_b32 m0, s49
	ds_read_b128 v[218:221], v165
	ds_read_b128 v[222:225], v165 offset:1024
	ds_read_b128 v[226:229], v165 offset:2048
	ds_read_b128 v[230:233], v165 offset:3072
	global_load_lds_dwordx4 v[190:191], off
	v_lshl_add_u64 v[190:191], v[234:235], 0, s[30:31]
	s_add_i32 m0, s49, 0x2000
	s_nop 0
	global_load_lds_dwordx4 v[190:191], off
	s_barrier
	s_waitcnt lgkmcnt(0)
	s_setprio 1
	s_waitcnt lgkmcnt(0)
	v_mfma_f32_16x16x32_bf16 v[108:111], v[218:221], v[182:185], v[108:111]
	v_mfma_f32_16x16x32_bf16 v[104:107], v[226:229], v[182:185], v[104:107]
	v_mfma_f32_16x16x32_bf16 v[92:95], v[218:221], v[194:197], v[92:95]
	v_mfma_f32_16x16x32_bf16 v[88:91], v[226:229], v[194:197], v[88:91]
	v_mfma_f32_16x16x32_bf16 v[76:79], v[218:221], v[202:205], v[76:79]
	v_mfma_f32_16x16x32_bf16 v[72:75], v[226:229], v[202:205], v[72:75]
	v_mfma_f32_16x16x32_bf16 v[68:71], v[218:221], v[210:213], v[68:71]
	v_mfma_f32_16x16x32_bf16 v[64:67], v[226:229], v[210:213], v[64:67]
	v_mfma_f32_16x16x32_bf16 v[108:111], v[222:225], v[186:189], v[108:111]
	v_mfma_f32_16x16x32_bf16 v[104:107], v[230:233], v[186:189], v[104:107]
	v_mfma_f32_16x16x32_bf16 v[92:95], v[222:225], v[198:201], v[92:95]
	v_mfma_f32_16x16x32_bf16 v[88:91], v[230:233], v[198:201], v[88:91]
	v_mfma_f32_16x16x32_bf16 v[76:79], v[222:225], v[206:209], v[76:79]
	v_mfma_f32_16x16x32_bf16 v[72:75], v[230:233], v[206:209], v[72:75]
	v_mfma_f32_16x16x32_bf16 v[68:71], v[222:225], v[214:217], v[68:71]
	v_mfma_f32_16x16x32_bf16 v[64:67], v[230:233], v[214:217], v[64:67]
	s_setprio 0
	s_mov_b32 m0, s60
	v_lshl_add_u64 v[190:191], v[236:237], 0, s[30:31]
	s_barrier
	ds_read_b128 v[182:185], v164 offset:49152
	ds_read_b128 v[186:189], v164 offset:50176
	ds_read_b128 v[194:197], v164 offset:51200
	ds_read_b128 v[198:201], v164 offset:52224
	ds_read_b128 v[202:205], v164 offset:53248
	ds_read_b128 v[206:209], v164 offset:54272
	ds_read_b128 v[210:213], v164 offset:55296
	ds_read_b128 v[214:217], v164 offset:56320
	global_load_lds_dwordx4 v[190:191], off
	v_lshl_add_u64 v[190:191], v[238:239], 0, s[30:31]
	s_mov_b32 m0, s61
	s_nop 0
	global_load_lds_dwordx4 v[190:191], off
	s_barrier
; #define G_STAGE(bufoff, gbase, voff) do { _Pragma("unroll") for (int _i = 0; _i < 2; ++_i) \
;         __builtin_amdgcn_global_load_lds((const unsigned*)((const char*)(gbase) + (voff)[_i]), (LAS unsigned*)(lds + (bufoff) + ldsw + _i * 8192), 16, 0, 0); } while (0)
; #define G_MMA(ai, bj, At, Bt) do { __builtin_amdgcn_s_setprio(1); _Pragma("unroll") for (int m = 0; m < 4; ++m) _Pragma("unroll") for (int n = 0; n < 2; ++n) _Pragma("unroll") for (int k = 0; k < 2; ++k) \
;         acc[ai][bj][m][n] = __builtin_amdgcn_mfma_f32_16x16x32_bf16(Bt[n][k], At[m][k], acc[ai][bj][m][n], 0, 0, 0); __builtin_amdgcn_s_setprio(0); } while (0)
; #define G_WAIT_V(n) asm volatile("s_waitcnt vmcnt(" #n ")" ::: "memory")
; #define G_WAIT_L(n) asm volatile("s_waitcnt lgkmcnt(" #n ")" ::: "memory")
; #define G_BAR __builtin_amdgcn_s_barrier()
; #define G_SCHED __builtin_amdgcn_sched_barrier(0)
; template <bool PERM, class Dec, class Epi>
; DI void gemm_phase(LAS unsigned char* lds, const int nM, const int nN, const int K, const int lda, const int ldb, const Dec& dec, const Epi& epi, const int vb, const int panel = -1) {
;     ...
;             G_BAR; G_WAIT_L(0); G_MMA(1, 0, At, B0); G_BAR; G_SCHED;
;             G_STAGE(G_SB(1, 1), b3 + hstepB, voffB);
;             G_WAIT_V(6); G_BAR; G_MMA(1, 1, At, B1); G_BAR;
;         }
	s_waitcnt lgkmcnt(0)
	s_setprio 1
	s_waitcnt lgkmcnt(0)
	v_mfma_f32_16x16x32_bf16 v[60:63], v[166:169], v[182:185], v[60:63]
	v_mfma_f32_16x16x32_bf16 v[56:59], v[174:177], v[182:185], v[56:59]
	v_mfma_f32_16x16x32_bf16 v[52:55], v[166:169], v[194:197], v[52:55]
	v_mfma_f32_16x16x32_bf16 v[48:51], v[174:177], v[194:197], v[48:51]
	v_mfma_f32_16x16x32_bf16 v[36:39], v[166:169], v[202:205], v[36:39]
	v_mfma_f32_16x16x32_bf16 v[32:35], v[174:177], v[202:205], v[32:35]
	v_mfma_f32_16x16x32_bf16 v[20:23], v[166:169], v[210:213], v[20:23]
	v_mfma_f32_16x16x32_bf16 v[16:19], v[174:177], v[210:213], v[16:19]
	v_mfma_f32_16x16x32_bf16 v[60:63], v[170:173], v[186:189], v[60:63]
	v_mfma_f32_16x16x32_bf16 v[56:59], v[178:181], v[186:189], v[56:59]
	v_mfma_f32_16x16x32_bf16 v[52:55], v[170:173], v[198:201], v[52:55]
	v_mfma_f32_16x16x32_bf16 v[48:51], v[178:181], v[198:201], v[48:51]
	v_mfma_f32_16x16x32_bf16 v[36:39], v[170:173], v[206:209], v[36:39]
	v_mfma_f32_16x16x32_bf16 v[32:35], v[178:181], v[206:209], v[32:35]
	v_mfma_f32_16x16x32_bf16 v[20:23], v[170:173], v[214:217], v[20:23]
	v_mfma_f32_16x16x32_bf16 v[16:19], v[178:181], v[214:217], v[16:19]
	s_setprio 0
	s_barrier
	s_add_u32 s46, s46, 0x40080
	s_addc_u32 s47, s47, 0
	s_add_i32 s48, s48, s55
	v_lshl_add_u64 v[166:167], s[46:47], 0, v[138:139]
	s_mov_b32 m0, s48
	s_nop 0
	global_load_lds_dwordx4 v[166:167], off
	v_lshl_add_u64 v[166:167], s[46:47], 0, v[134:135]
	s_add_i32 m0, s48, 0x2000
	s_nop 0
	global_load_lds_dwordx4 v[166:167], off
	s_waitcnt vmcnt(6)
	s_barrier
	s_setprio 1
	v_mfma_f32_16x16x32_bf16 v[44:47], v[218:221], v[182:185], v[44:47]
	v_mfma_f32_16x16x32_bf16 v[40:43], v[226:229], v[182:185], v[40:43]
	v_mfma_f32_16x16x32_bf16 v[28:31], v[218:221], v[194:197], v[28:31]
	v_mfma_f32_16x16x32_bf16 v[24:27], v[226:229], v[194:197], v[24:27]
	v_mfma_f32_16x16x32_bf16 v[12:15], v[218:221], v[202:205], v[12:15]
	v_mfma_f32_16x16x32_bf16 v[8:11], v[226:229], v[202:205], v[8:11]
	v_mfma_f32_16x16x32_bf16 v[4:7], v[218:221], v[210:213], v[4:7]
	v_mfma_f32_16x16x32_bf16 v[0:3], v[226:229], v[210:213], v[0:3]
	v_mfma_f32_16x16x32_bf16 v[44:47], v[222:225], v[186:189], v[44:47]
	v_mfma_f32_16x16x32_bf16 v[40:43], v[230:233], v[186:189], v[40:43]
	v_mfma_f32_16x16x32_bf16 v[28:31], v[222:225], v[198:201], v[28:31]
	v_mfma_f32_16x16x32_bf16 v[24:27], v[230:233], v[198:201], v[24:27]
	v_mfma_f32_16x16x32_bf16 v[12:15], v[222:225], v[206:209], v[12:15]
	v_mfma_f32_16x16x32_bf16 v[8:11], v[230:233], v[206:209], v[8:11]
	v_mfma_f32_16x16x32_bf16 v[4:7], v[222:225], v[214:217], v[4:7]
	v_mfma_f32_16x16x32_bf16 v[0:3], v[230:233], v[214:217], v[0:3]
	s_setprio 0
	s_add_i32 s79, s79, 2
	s_add_u32 s44, s44, 0x100
	s_addc_u32 s45, s45, 0
	s_add_u32 s76, s76, 0x100
	s_addc_u32 s77, s77, 0
	s_cmp_gt_u32 s79, 13
	s_barrier
	s_cbranch_scc0 .LBB0_182
; DI unsigned pk2(float a, float b) { f32x2 v = {a, b}; bf2_t r = __builtin_convertvector(v, bf2_t); return __builtin_bit_cast(unsigned, r); }
; DI float sigm(float x) { return __builtin_amdgcn_rcpf(1.f + __expf(-x)); }
; DI float silu_(float x) { return x * __builtin_amdgcn_rcpf(1.f + __expf(-x)); }
; template <int ACT>
; DI void epi_bf16(const f32x4 (&acc)[2][2][4][2], bf16_t* O, const int ldc, int wr, int wc, int fr, int fq, const float* ssrow = nullptr) {
; #pragma unroll
;     for (int ai = 0; ai < 2; ++ai)
; #pragma unroll
;         for (int m = 0; m < 4; ++m) {
;             bf16_t* rowp = O + (size_t)(ai * HALF + wr * 64 + m * 16 + fr) * ldc + wc * 32 + 8 * fq;
;             const float rsc = ssrow ? __builtin_amdgcn_rsqf(ssrow[ai * HALF + wr * 64 + m * 16 + fr] * (1.f / 1024.f) + EPS_) : 1.f;
; #pragma unroll
;             for (int bj = 0; bj < 2; ++bj) {
;                 f32x4 v0 = acc[ai][bj][m][0] * rsc, v1 = acc[ai][bj][m][1] * rsc;
;                 if (ACT == 1) {
; #pragma unroll
;                     for (int j = 0; j < 4; ++j) { v0[j] = silu_(v0[j]); v1[j] = silu_(v1[j]); } }
;                 if (ACT == 2) {
; #pragma unroll
;                     for (int j = 0; j < 4; ++j) { v0[j] = sigm(v0[j]); v1[j] = sigm(v1[j]); } }
;                 u32x4 w; w[0] = pk2(v0[0], v0[1]); w[1] = pk2(v0[2], v0[3]); w[2] = pk2(v1[0], v1[1]); w[3] = pk2(v1[2], v1[3]);
;                 *(u32x4*)(rowp + bj * HALF) = w;
;             }
; __global__ void __launch_bounds__(512) hybrid_fwd(Params p) {
;     ...
;           [=](int pm, int pn, const char*& a, const char*& b) { a = A + (size_t)pm * 256 * 1024 * 2; b = B + (size_t)pn * 256 * 1024 * 2; },
;           [=](const f32x4 (&acc)[2][2][4][2], int pm, int pn, int wr, int wc, int fr, int fq) { epi_bf16<0>(acc, RA + (size_t)pm * 256 * 2048 + pn * 256, 2048, wr, wc, fr, fq); }, vb); }
	s_ashr_i32 s23, s22, 31
	s_lshl_b64 s[22:23], s[22:23], 20
	s_add_u32 s3, s86, s22
	s_addc_u32 s35, s87, s23
	s_lshl_b32 s22, s70, 8
	s_ashr_i32 s23, s22, 31
	s_lshl_b64 s[22:23], s[22:23], 1
	s_add_u32 s3, s3, s22
	s_addc_u32 s23, s35, s23
	s_add_u32 s22, s3, s67
	s_addc_u32 s23, s23, 0
	v_lshl_add_u64 v[166:167], s[22:23], 0, v[128:129]
	v_lshl_add_u64 v[168:169], v[166:167], 0, v[142:143]
	v_cvt_pk_bf16_f32 v108, v108, v109
	v_cvt_pk_bf16_f32 v109, v110, v111
	v_cvt_pk_bf16_f32 v110, v104, v105
	v_cvt_pk_bf16_f32 v111, v106, v107
	ds_bpermute_b32 v108, v241, v108
	ds_bpermute_b32 v109, v241, v109
	ds_bpermute_b32 v110, v241, v110
	ds_bpermute_b32 v111, v241, v111
	v_cvt_pk_bf16_f32 v68, v68, v69
	v_cvt_pk_bf16_f32 v69, v70, v71
	v_cvt_pk_bf16_f32 v70, v64, v65
	v_lshl_add_u64 v[64:65], v[166:167], 0, v[150:151]
	v_cvt_pk_bf16_f32 v44, v44, v45
	v_cvt_pk_bf16_f32 v45, v46, v47
	v_cvt_pk_bf16_f32 v46, v40, v41
	v_cvt_pk_bf16_f32 v47, v42, v43
	ds_bpermute_b32 v44, v241, v44
	ds_bpermute_b32 v45, v241, v45
	ds_bpermute_b32 v46, v241, v46
	ds_bpermute_b32 v47, v241, v47
	s_waitcnt lgkmcnt(4)
	global_store_dwordx4 v[168:169], v[108:111], off offset:256
	v_cvt_pk_bf16_f32 v92, v92, v93
	v_cvt_pk_bf16_f32 v93, v94, v95
	v_lshl_add_u64 v[108:109], v[166:167], 0, v[144:145]
	v_cvt_pk_bf16_f32 v94, v88, v89
	v_cvt_pk_bf16_f32 v95, v90, v91
	ds_bpermute_b32 v92, v241, v92
	ds_bpermute_b32 v93, v241, v93
	ds_bpermute_b32 v94, v241, v94
	ds_bpermute_b32 v95, v241, v95
	s_waitcnt lgkmcnt(4)
	global_store_dwordx4 v[64:65], v[44:47], off offset:256
	v_cvt_pk_bf16_f32 v28, v28, v29
	v_cvt_pk_bf16_f32 v29, v30, v31
	v_lshl_add_u64 v[44:45], v[166:167], 0, v[152:153]
	v_cvt_pk_bf16_f32 v30, v24, v25
	v_cvt_pk_bf16_f32 v31, v26, v27
	ds_bpermute_b32 v28, v241, v28
	ds_bpermute_b32 v29, v241, v29
	ds_bpermute_b32 v30, v241, v30
	ds_bpermute_b32 v31, v241, v31
	s_waitcnt lgkmcnt(4)
	global_store_dwordx4 v[108:109], v[92:95], off offset:256
	v_cvt_pk_bf16_f32 v76, v76, v77
	v_cvt_pk_bf16_f32 v77, v78, v79
	v_lshl_add_u64 v[92:93], v[166:167], 0, v[146:147]
	v_cvt_pk_bf16_f32 v78, v72, v73
	v_cvt_pk_bf16_f32 v79, v74, v75
	ds_bpermute_b32 v76, v241, v76
	ds_bpermute_b32 v77, v241, v77
	ds_bpermute_b32 v78, v241, v78
	ds_bpermute_b32 v79, v241, v79
	s_waitcnt lgkmcnt(4)
	global_store_dwordx4 v[44:45], v[28:31], off offset:256
	v_cvt_pk_bf16_f32 v12, v12, v13
	v_cvt_pk_bf16_f32 v13, v14, v15
	v_lshl_add_u64 v[28:29], v[166:167], 0, v[154:155]
	v_cvt_pk_bf16_f32 v14, v8, v9
	v_cvt_pk_bf16_f32 v15, v10, v11
	ds_bpermute_b32 v12, v241, v12
	ds_bpermute_b32 v13, v241, v13
	ds_bpermute_b32 v14, v241, v14
	ds_bpermute_b32 v15, v241, v15
	v_cvt_pk_bf16_f32 v124, v124, v125
	v_cvt_pk_bf16_f32 v125, v126, v127
	v_cvt_pk_bf16_f32 v126, v120, v121
	v_cvt_pk_bf16_f32 v127, v122, v123
	ds_bpermute_b32 v124, v241, v124
	ds_bpermute_b32 v125, v241, v125
	ds_bpermute_b32 v126, v241, v126
	ds_bpermute_b32 v127, v241, v127
	v_cvt_pk_bf16_f32 v104, v116, v117
	v_cvt_pk_bf16_f32 v105, v118, v119
	v_cvt_pk_bf16_f32 v106, v112, v113
	v_cvt_pk_bf16_f32 v107, v114, v115
	v_cvt_pk_bf16_f32 v88, v100, v101
	v_cvt_pk_bf16_f32 v89, v102, v103
	v_cvt_pk_bf16_f32 v90, v96, v97
	v_cvt_pk_bf16_f32 v91, v98, v99
	s_waitcnt lgkmcnt(8)
	global_store_dwordx4 v[92:93], v[76:79], off offset:256
	ds_bpermute_b32 v104, v241, v104
	ds_bpermute_b32 v105, v241, v105
	ds_bpermute_b32 v106, v241, v106
	ds_bpermute_b32 v107, v241, v107
	v_cvt_pk_bf16_f32 v72, v84, v85
	v_cvt_pk_bf16_f32 v73, v86, v87
	v_lshl_add_u64 v[76:77], v[166:167], 0, v[148:149]
	v_cvt_pk_bf16_f32 v74, v80, v81
	v_cvt_pk_bf16_f32 v75, v82, v83
	v_cvt_pk_bf16_f32 v71, v66, v67
	v_cvt_pk_bf16_f32 v60, v60, v61
	v_cvt_pk_bf16_f32 v61, v62, v63
	v_cvt_pk_bf16_f32 v62, v56, v57
	v_cvt_pk_bf16_f32 v63, v58, v59
	v_cvt_pk_bf16_f32 v40, v52, v53
	v_cvt_pk_bf16_f32 v41, v54, v55
	v_cvt_pk_bf16_f32 v42, v48, v49
	v_cvt_pk_bf16_f32 v43, v50, v51
	v_cvt_pk_bf16_f32 v24, v36, v37
	v_cvt_pk_bf16_f32 v25, v38, v39
	v_cvt_pk_bf16_f32 v26, v32, v33
	v_cvt_pk_bf16_f32 v27, v34, v35
	s_waitcnt lgkmcnt(8)
	global_store_dwordx4 v[28:29], v[12:15], off offset:256
	ds_bpermute_b32 v88, v241, v88
	ds_bpermute_b32 v89, v241, v89
	ds_bpermute_b32 v90, v241, v90
	ds_bpermute_b32 v91, v241, v91
	v_cvt_pk_bf16_f32 v8, v20, v21
	v_cvt_pk_bf16_f32 v9, v22, v23
	v_lshl_add_u64 v[12:13], v[166:167], 0, v[156:157]
	v_cvt_pk_bf16_f32 v10, v16, v17
	v_cvt_pk_bf16_f32 v11, v18, v19
	v_cvt_pk_bf16_f32 v4, v4, v5
	v_cvt_pk_bf16_f32 v5, v6, v7
	v_cvt_pk_bf16_f32 v6, v0, v1
	v_cvt_pk_bf16_f32 v7, v2, v3
	s_and_b64 vcc, exec, s[40:41]
	s_mov_b32 s22, s34
	s_mov_b32 s70, s2
	s_mov_b64 s[44:45], s[36:37]
	s_mov_b64 s[46:47], s[42:43]
	s_waitcnt lgkmcnt(8)
	global_store_dwordx4 v[168:169], v[124:127], off
	ds_bpermute_b32 v72, v241, v72
	ds_bpermute_b32 v73, v241, v73
	ds_bpermute_b32 v74, v241, v74
	ds_bpermute_b32 v75, v241, v75
	s_waitcnt lgkmcnt(8)
	global_store_dwordx4 v[108:109], v[104:107], off
	ds_bpermute_b32 v68, v241, v68
	ds_bpermute_b32 v69, v241, v69
	ds_bpermute_b32 v70, v241, v70
	ds_bpermute_b32 v71, v241, v71
	s_waitcnt lgkmcnt(8)
	global_store_dwordx4 v[92:93], v[88:91], off
	ds_bpermute_b32 v60, v241, v60
	ds_bpermute_b32 v61, v241, v61
	ds_bpermute_b32 v62, v241, v62
	ds_bpermute_b32 v63, v241, v63
	s_waitcnt lgkmcnt(8)
	global_store_dwordx4 v[76:77], v[72:75], off
	ds_bpermute_b32 v40, v241, v40
	ds_bpermute_b32 v41, v241, v41
	ds_bpermute_b32 v42, v241, v42
	ds_bpermute_b32 v43, v241, v43
	s_waitcnt lgkmcnt(8)
	global_store_dwordx4 v[76:77], v[68:71], off offset:256
	ds_bpermute_b32 v24, v241, v24
	ds_bpermute_b32 v25, v241, v25
	ds_bpermute_b32 v26, v241, v26
	ds_bpermute_b32 v27, v241, v27
	s_waitcnt lgkmcnt(8)
	global_store_dwordx4 v[64:65], v[60:63], off
	ds_bpermute_b32 v8, v241, v8
	ds_bpermute_b32 v9, v241, v9
	ds_bpermute_b32 v10, v241, v10
	ds_bpermute_b32 v11, v241, v11
	s_waitcnt lgkmcnt(8)
	global_store_dwordx4 v[44:45], v[40:43], off
	ds_bpermute_b32 v4, v241, v4
	ds_bpermute_b32 v5, v241, v5
	ds_bpermute_b32 v6, v241, v6
	ds_bpermute_b32 v7, v241, v7
	s_waitcnt lgkmcnt(8)
	global_store_dwordx4 v[28:29], v[24:27], off
	s_waitcnt lgkmcnt(4)
	global_store_dwordx4 v[12:13], v[8:11], off
	s_waitcnt lgkmcnt(0)
	global_store_dwordx4 v[12:13], v[4:7], off offset:256
	s_cbranch_vccz .LBB0_179
	s_waitcnt vmcnt(0)
	s_cmpk_gt_u32 s54, 0xff
	s_cbranch_scc1 .LBB0_186
	s_barrier

; #define G_STAGE(bufoff, gbase, voff) do { _Pragma("unroll") for (int _i = 0; _i < 2; ++_i) \
;         __builtin_amdgcn_global_load_lds((const unsigned*)((const char*)(gbase) + (voff)[_i]), (LAS unsigned*)(lds + (bufoff) + ldsw + _i * 8192), 16, 0, 0); } while (0)
; #define G_WAIT_V(n) asm volatile("s_waitcnt vmcnt(" #n ")" ::: "memory")
; #define G_BAR __builtin_amdgcn_s_barrier()
; template <bool PERM, class Dec, class Epi>
; DI void gemm_phase(LAS unsigned char* lds, const int nM, const int nN, const int K, const int lda, const int ldb, const Dec& dec, const Epi& epi, const int vb, const int panel = -1) {
;     ...
;     G_STAGE(G_SB(0, 0), cB, voffB); G_STAGE(G_SA(0, 0), cA, voffA); G_STAGE(G_SB(0, 1), cB + hstepB, voffB); G_STAGE(G_SA(0, 1), cA + hstepA, voffA);
;     if (wr == 1) G_BAR;
;     G_WAIT_V(4); G_BAR;
;     G_STAGE(G_SB(1, 0), cB + kstep, voffB); G_STAGE(G_SA(1, 0), cA + kstep, voffA); G_STAGE(G_SB(1, 1), cB + hstepB + kstep, voffB);
;     G_WAIT_V(6); G_BAR;
; template <int ACT>
; DI void epi_bf16(const f32x4 (&acc)[2][2][4][2], bf16_t* O, const int ldc, int wr, int wc, int fr, int fq, const float* ssrow = nullptr) {
; #pragma unroll
;     for (int ai = 0; ai < 2; ++ai)
; #pragma unroll
;         for (int m = 0; m < 4; ++m) {
;             bf16_t* rowp = O + (size_t)(ai * HALF + wr * 64 + m * 16 + fr) * ldc + wc * 32 + 8 * fq;
.LBB0_311:
	s_lshl_b32 s0, s38, 5
	s_and_b32 s3, s0, 0x60
	s_add_i32 m0, s55, 0x18000
	v_lshl_add_u64 v[6:7], v[6:7], 0, s[56:57]
	s_lshl_b32 s2, s30, 13
	s_lshl_b32 s38, s3, 7
	s_waitcnt vmcnt(4)
	s_barrier
	global_load_lds_dwordx4 v[6:7], off
	v_lshl_add_u64 v[4:5], v[4:5], 0, s[56:57]
	s_add_i32 m0, s55, 0x1a000
	s_add_i32 s82, s55, 0x8000
	s_add_i32 s83, s55, 0xa000
	global_load_lds_dwordx4 v[4:5], off
	v_lshl_add_u64 v[2:3], v[2:3], 0, s[56:57]
	s_mov_b32 m0, s82
	s_add_u32 s0, s58, 0x20080
	global_load_lds_dwordx4 v[2:3], off
	v_lshl_add_u64 v[0:1], v[0:1], 0, s[56:57]
	s_mov_b32 m0, s83
	s_addc_u32 s1, s59, 0
	global_load_lds_dwordx4 v[0:1], off
	s_add_i32 m0, s55, 0x1c000
	v_lshl_add_u64 v[0:1], s[0:1], 0, v[136:137]
	global_load_lds_dwordx4 v[0:1], off
	v_lshl_add_u64 v[0:1], s[0:1], 0, v[140:141]
	s_add_i32 m0, s55, 0x1e000
	v_readlane_b32 s0, v245, 25
	global_load_lds_dwordx4 v[0:1], off
	v_lshrrev_b32_e32 v0, 1, v9
	v_and_b32_e32 v0, 24, v0
	v_and_b32_e32 v1, 15, v9
	v_lshlrev_b32_e32 v2, 1, v0
	v_bfe_u32 v142, v9, 2, 4
	v_lshl_or_b32 v142, s30, 6, v142
	v_lshl_or_b32 v1, v1, 6, v2
	v_lshlrev_b32_e32 v2, 2, v9
	v_and_b32_e32 v2, 32, v2
	v_bitop3_b32 v3, v1, s2, v2 bitop3:0xde
	v_bitop3_b32 v164, v1, s38, v2 bitop3:0xde
	v_lshlrev_b32_e32 v1, 15, v8
	v_and_b32_e32 v1, 0xffff0000, v1
	v_lshl_add_u32 v1, v10, 12, v1
	v_and_b32_e32 v2, 1, v8
	v_lshl_or_b32 v1, v2, 6, v1
	v_lshl_add_u32 v158, v11, 1, v1
	v_lshlrev_b32_e32 v1, 15, v12
	v_and_b32_e32 v1, 0xffff0000, v1
	s_waitcnt vmcnt(6)
	v_lshl_add_u32 v1, v13, 12, v1
	v_and_b32_e32 v2, 1, v12
	v_or_b32_e32 v144, 16, v142
	v_or_b32_e32 v146, 32, v142
	v_or_b32_e32 v148, 48, v142
	v_add_u32_e32 v150, 0x80, v142
	v_add_u32_e32 v152, 0x90, v142
	v_add_u32_e32 v154, 0xa0, v142
	v_add_u32_e32 v156, 0xb0, v142
	v_lshl_or_b32 v1, v2, 6, v1
	v_ashrrev_i32_e32 v143, 31, v142
	v_ashrrev_i32_e32 v145, 31, v144
	v_ashrrev_i32_e32 v147, 31, v146
	v_ashrrev_i32_e32 v149, 31, v148
	v_ashrrev_i32_e32 v151, 31, v150
	v_ashrrev_i32_e32 v153, 31, v152
	v_ashrrev_i32_e32 v155, 31, v154
	v_ashrrev_i32_e32 v157, 31, v156
	v_mov_b32_e32 v159, v129
	v_lshl_add_u32 v160, v14, 1, v1
	v_mov_b32_e32 v161, v129
	s_mov_b32 s86, 0
	v_add_u32_e32 v165, 0, v3
	s_lshl_b32 s87, s3, 1
	v_mbcnt_lo_u32_b32 v241, -1, 0
	v_mbcnt_hi_u32_b32 v241, -1, v241
	v_and_b32_e32 v128, 3, v241
	v_lshlrev_b32_e32 v128, 4, v128
	v_and_b32_e32 v241, 60, v241
	v_lshl_or_b32 v241, v128, 2, v241
	s_mov_b32 s70, s34
	s_mov_b32 s90, s0
	s_barrier
	v_readlane_b32 s1, v245, 26
	s_branch .LBB0_313
; DI unsigned pk2(float a, float b) { f32x2 v = {a, b}; bf2_t r = __builtin_convertvector(v, bf2_t); return __builtin_bit_cast(unsigned, r); }
; DI float sigm(float x) { return __builtin_amdgcn_rcpf(1.f + __expf(-x)); }
; DI float silu_(float x) { return x * __builtin_amdgcn_rcpf(1.f + __expf(-x)); }
; template <int ACT>
; DI void epi_bf16(const f32x4 (&acc)[2][2][4][2], bf16_t* O, const int ldc, int wr, int wc, int fr, int fq, const float* ssrow = nullptr) {
; #pragma unroll
;     for (int ai = 0; ai < 2; ++ai)
; #pragma unroll
;         for (int m = 0; m < 4; ++m) {
;             bf16_t* rowp = O + (size_t)(ai * HALF + wr * 64 + m * 16 + fr) * ldc + wc * 32 + 8 * fq;
;             const float rsc = ssrow ? __builtin_amdgcn_rsqf(ssrow[ai * HALF + wr * 64 + m * 16 + fr] * (1.f / 1024.f) + EPS_) : 1.f;
; #pragma unroll
;             for (int bj = 0; bj < 2; ++bj) {
;                 f32x4 v0 = acc[ai][bj][m][0] * rsc, v1 = acc[ai][bj][m][1] * rsc;
;                 if (ACT == 1) {
; #pragma unroll
;                     for (int j = 0; j < 4; ++j) { v0[j] = silu_(v0[j]); v1[j] = silu_(v1[j]); } }
;                 if (ACT == 2) {
; #pragma unroll
;                     for (int j = 0; j < 4; ++j) { v0[j] = sigm(v0[j]); v1[j] = sigm(v1[j]); } }
;                 u32x4 w; w[0] = pk2(v0[0], v0[1]); w[1] = pk2(v0[2], v0[3]); w[2] = pk2(v1[0], v1[1]); w[3] = pk2(v1[2], v1[3]);
;                 *(u32x4*)(rowp + bj * HALF) = w;
;             }
; __global__ void __launch_bounds__(512) hybrid_fwd(Params p) {
;     ...
;           [=](const f32x4 (&acc)[2][2][4][2], int pm, int pn, int wr, int wc, int fr, int fq) {
;               if (pn < 8) epi_bf16<0>(acc, OUTB + (size_t)(pn & 1) * T_ * 1024 + (size_t)pm * 256 * 1024 + (pn >> 1) * 256, 1024, wr, wc, fr, fq);
;               else epi_bf16<0>(acc, RC + (size_t)pm * 256 * 2048 + (pn - 8) * 256, 2048, wr, wc, fr, fq); }, vb); }
.LBB0_312:
	s_add_u32 s58, s58, s87
	s_addc_u32 s59, s59, 0
	v_lshl_add_u64 v[166:167], s[58:59], 0, v[128:129]
	v_lshlrev_b64 v[168:169], s22, v[142:143]
	v_lshl_add_u64 v[168:169], v[166:167], 0, v[168:169]
	v_cvt_pk_bf16_f32 v108, v108, v109
	v_cvt_pk_bf16_f32 v109, v110, v111
	v_cvt_pk_bf16_f32 v110, v104, v105
	v_cvt_pk_bf16_f32 v111, v106, v107
	ds_bpermute_b32 v108, v241, v108
	ds_bpermute_b32 v109, v241, v109
	ds_bpermute_b32 v110, v241, v110
	ds_bpermute_b32 v111, v241, v111
	v_lshlrev_b64 v[104:105], s22, v[144:145]
	v_cvt_pk_bf16_f32 v124, v124, v125
	v_cvt_pk_bf16_f32 v125, v126, v127
	v_cvt_pk_bf16_f32 v126, v120, v121
	v_cvt_pk_bf16_f32 v127, v122, v123
	ds_bpermute_b32 v124, v241, v124
	ds_bpermute_b32 v125, v241, v125
	ds_bpermute_b32 v126, v241, v126
	ds_bpermute_b32 v127, v241, v127
	s_waitcnt lgkmcnt(4)
	global_store_dwordx4 v[168:169], v[108:111], off offset:256
	v_cvt_pk_bf16_f32 v92, v92, v93
	v_cvt_pk_bf16_f32 v93, v94, v95
	v_lshl_add_u64 v[108:109], v[166:167], 0, v[104:105]
	v_cvt_pk_bf16_f32 v94, v88, v89
	v_cvt_pk_bf16_f32 v95, v90, v91
	ds_bpermute_b32 v92, v241, v92
	ds_bpermute_b32 v93, v241, v93
	ds_bpermute_b32 v94, v241, v94
	ds_bpermute_b32 v95, v241, v95
	v_lshlrev_b64 v[88:89], s22, v[146:147]
	s_waitcnt lgkmcnt(4)
	global_store_dwordx4 v[168:169], v[124:127], off
	v_cvt_pk_bf16_f32 v104, v116, v117
	v_cvt_pk_bf16_f32 v105, v118, v119
	v_cvt_pk_bf16_f32 v106, v112, v113
	v_cvt_pk_bf16_f32 v107, v114, v115
	ds_bpermute_b32 v104, v241, v104
	ds_bpermute_b32 v105, v241, v105
	ds_bpermute_b32 v106, v241, v106
	ds_bpermute_b32 v107, v241, v107
	s_waitcnt lgkmcnt(4)
	global_store_dwordx4 v[108:109], v[92:95], off offset:256
	v_cvt_pk_bf16_f32 v76, v76, v77
	v_cvt_pk_bf16_f32 v77, v78, v79
	v_lshl_add_u64 v[92:93], v[166:167], 0, v[88:89]
	v_cvt_pk_bf16_f32 v78, v72, v73
	v_cvt_pk_bf16_f32 v79, v74, v75
	ds_bpermute_b32 v76, v241, v76
	ds_bpermute_b32 v77, v241, v77
	ds_bpermute_b32 v78, v241, v78
	ds_bpermute_b32 v79, v241, v79
	v_lshlrev_b64 v[72:73], s22, v[148:149]
	v_cvt_pk_bf16_f32 v68, v68, v69
	v_cvt_pk_bf16_f32 v69, v70, v71
	v_cvt_pk_bf16_f32 v70, v64, v65
	v_lshlrev_b64 v[64:65], s22, v[150:151]
	s_waitcnt lgkmcnt(4)
	global_store_dwordx4 v[108:109], v[104:107], off
	v_cvt_pk_bf16_f32 v88, v100, v101
	v_cvt_pk_bf16_f32 v89, v102, v103
	v_cvt_pk_bf16_f32 v90, v96, v97
	v_cvt_pk_bf16_f32 v91, v98, v99
	ds_bpermute_b32 v88, v241, v88
	ds_bpermute_b32 v89, v241, v89
	ds_bpermute_b32 v90, v241, v90
	ds_bpermute_b32 v91, v241, v91
	s_waitcnt lgkmcnt(4)
	global_store_dwordx4 v[92:93], v[76:79], off offset:256
	v_cvt_pk_bf16_f32 v74, v80, v81
	v_cvt_pk_bf16_f32 v75, v82, v83
	v_lshl_add_u64 v[76:77], v[166:167], 0, v[72:73]
	v_cvt_pk_bf16_f32 v72, v84, v85
	v_cvt_pk_bf16_f32 v73, v86, v87
	ds_bpermute_b32 v72, v241, v72
	ds_bpermute_b32 v73, v241, v73
	ds_bpermute_b32 v74, v241, v74
	ds_bpermute_b32 v75, v241, v75
	v_cvt_pk_bf16_f32 v71, v66, v67
	ds_bpermute_b32 v68, v241, v68
	ds_bpermute_b32 v69, v241, v69
	ds_bpermute_b32 v70, v241, v70
	ds_bpermute_b32 v71, v241, v71
	v_lshl_add_u64 v[64:65], v[166:167], 0, v[64:65]
	v_cvt_pk_bf16_f32 v44, v44, v45
	v_cvt_pk_bf16_f32 v45, v46, v47
	v_cvt_pk_bf16_f32 v46, v40, v41
	v_cvt_pk_bf16_f32 v47, v42, v43
	v_lshlrev_b64 v[40:41], s22, v[152:153]
	s_waitcnt lgkmcnt(8)
	global_store_dwordx4 v[92:93], v[88:91], off
	ds_bpermute_b32 v44, v241, v44
	ds_bpermute_b32 v45, v241, v45
	ds_bpermute_b32 v46, v241, v46
	ds_bpermute_b32 v47, v241, v47
	s_waitcnt lgkmcnt(8)
	global_store_dwordx4 v[76:77], v[72:75], off
	s_waitcnt lgkmcnt(4)
	global_store_dwordx4 v[76:77], v[68:71], off offset:256
	v_cvt_pk_bf16_f32 v60, v60, v61
	v_cvt_pk_bf16_f32 v61, v62, v63
	v_cvt_pk_bf16_f32 v62, v56, v57
	v_cvt_pk_bf16_f32 v63, v58, v59
	ds_bpermute_b32 v60, v241, v60
	ds_bpermute_b32 v61, v241, v61
	ds_bpermute_b32 v62, v241, v62
	ds_bpermute_b32 v63, v241, v63
	s_waitcnt lgkmcnt(4)
	global_store_dwordx4 v[64:65], v[44:47], off offset:256
	v_cvt_pk_bf16_f32 v28, v28, v29
	v_cvt_pk_bf16_f32 v29, v30, v31
	v_lshl_add_u64 v[44:45], v[166:167], 0, v[40:41]
	v_cvt_pk_bf16_f32 v30, v24, v25
	v_cvt_pk_bf16_f32 v31, v26, v27
	ds_bpermute_b32 v28, v241, v28
	ds_bpermute_b32 v29, v241, v29
	ds_bpermute_b32 v30, v241, v30
	ds_bpermute_b32 v31, v241, v31
	v_lshlrev_b64 v[24:25], s22, v[154:155]
	s_waitcnt lgkmcnt(4)
	global_store_dwordx4 v[64:65], v[60:63], off
	v_cvt_pk_bf16_f32 v40, v52, v53
	v_cvt_pk_bf16_f32 v41, v54, v55
	v_cvt_pk_bf16_f32 v42, v48, v49
	v_cvt_pk_bf16_f32 v43, v50, v51
	ds_bpermute_b32 v40, v241, v40
	ds_bpermute_b32 v41, v241, v41
	ds_bpermute_b32 v42, v241, v42
	ds_bpermute_b32 v43, v241, v43
	s_waitcnt lgkmcnt(4)
	global_store_dwordx4 v[44:45], v[28:31], off offset:256
	v_cvt_pk_bf16_f32 v12, v12, v13
	v_cvt_pk_bf16_f32 v13, v14, v15
	v_lshl_add_u64 v[28:29], v[166:167], 0, v[24:25]
	v_cvt_pk_bf16_f32 v14, v8, v9
	v_cvt_pk_bf16_f32 v15, v10, v11
	ds_bpermute_b32 v12, v241, v12
	ds_bpermute_b32 v13, v241, v13
	ds_bpermute_b32 v14, v241, v14
	ds_bpermute_b32 v15, v241, v15
	v_lshlrev_b64 v[8:9], s22, v[156:157]
	s_waitcnt lgkmcnt(4)
	global_store_dwordx4 v[44:45], v[40:43], off
	v_cvt_pk_bf16_f32 v24, v36, v37
	v_cvt_pk_bf16_f32 v25, v38, v39
	v_cvt_pk_bf16_f32 v26, v32, v33
	v_cvt_pk_bf16_f32 v27, v34, v35
	ds_bpermute_b32 v24, v241, v24
	ds_bpermute_b32 v25, v241, v25
	ds_bpermute_b32 v26, v241, v26
	ds_bpermute_b32 v27, v241, v27
	s_waitcnt lgkmcnt(4)
	global_store_dwordx4 v[28:29], v[12:15], off offset:256
	v_cvt_pk_bf16_f32 v10, v16, v17
	v_cvt_pk_bf16_f32 v11, v18, v19
	v_lshl_add_u64 v[12:13], v[166:167], 0, v[8:9]
	v_cvt_pk_bf16_f32 v8, v20, v21
	v_cvt_pk_bf16_f32 v9, v22, v23
	ds_bpermute_b32 v8, v241, v8
	ds_bpermute_b32 v9, v241, v9
	ds_bpermute_b32 v10, v241, v10
	ds_bpermute_b32 v11, v241, v11
	v_cvt_pk_bf16_f32 v4, v4, v5
	v_cvt_pk_bf16_f32 v5, v6, v7
	v_cvt_pk_bf16_f32 v6, v0, v1
	v_cvt_pk_bf16_f32 v7, v2, v3
	ds_bpermute_b32 v4, v241, v4
	ds_bpermute_b32 v5, v241, v5
	ds_bpermute_b32 v6, v241, v6
	ds_bpermute_b32 v7, v241, v7
	s_and_b64 vcc, exec, s[38:39]
	s_mov_b32 s70, s60
	s_mov_b32 s90, s2
	s_mov_b64 s[22:23], s[0:1]
	s_mov_b64 s[58:59], s[66:67]
	s_waitcnt lgkmcnt(8)
	global_store_dwordx4 v[28:29], v[24:27], off
	s_waitcnt lgkmcnt(4)
	global_store_dwordx4 v[12:13], v[8:11], off
	s_waitcnt lgkmcnt(0)
	global_store_dwordx4 v[12:13], v[4:7], off offset:256
	s_cbranch_vccnz .LBB0_327
